# out-proj epilogue: residual stream loads/stores marked nt
# baseline (speedup 1.0000x reference)
; template <int TJ>
; DI void outproj_tile(const Params& p, int l, char* smem, int b, int trow0, int n0) {
;     ...
;     const float* gt = p.mod + ((size_t)l * 9 + (trow0 < SEQ ? b : 8)) * 3072 + 2048 + n0 + 64 * wf;
;     const float* xs = src_row(p, l, b, trow0 + 32 * TJ * wt) + n0 + 64 * wf;
;     float* xd = dst_row(p, b, trow0 + 32 * TJ * wt) + n0 + 64 * wf;
;     char* sb = smem + wave * 8192;
;     float4 xo[2][4 * TJ];
; #pragma unroll
;     for (int i = 0; i < 2; ++i)
; #pragma unroll
;         for (int it = 0; it < 4 * TJ; ++it) {
;             const int c = lane + 64 * it, row = c >> 3, f = 32 * i + 4 * ((c & 7) ^ (row & 7));
;             xo[i][it] = *(const float4*)(xs + (size_t)row * D + f);
;         }
; #pragma unroll
;     for (int i = 0; i < 2; ++i) {
; #pragma unroll
;         for (int j = 0; j < TJ; ++j)
; #pragma unroll
;             for (int q = 0; q < 4; ++q) {
;                 const int row = 32 * j + r, c16 = 2 * q + h;
;                 float4 y; y.x = acc[i][j][4 * q]; y.y = acc[i][j][4 * q + 1]; y.z = acc[i][j][4 * q + 2]; y.w = acc[i][j][4 * q + 3];
;                 *(float4*)(sb + row * 128 + ((c16 ^ (row & 7)) << 4)) = y;
;             }
.LBB0_18:
	global_load_dwordx2 v[70:71], v[70:71], off
	s_and_b64 s[6:7], s[6:7], exec
	s_cselect_b32 s6, s4, 8
	s_ashr_i32 s7, s6, 31
	s_mul_i32 s34, s60, 9
	s_add_u32 s6, s34, s6
	s_mul_hi_i32 s34, s60, 9
	s_addc_u32 s7, s34, s7
	s_mulk_i32 s7, 0x3000
	s_mul_hi_u32 s34, s6, 0x3000
	s_load_dwordx4 s[56:59], s[0:1], 0xa8
	v_lshlrev_b64 v[64:65], v64, s[4:5]
	s_add_i32 s34, s34, s7
	s_mulk_i32 s6, 0x3000
	s_waitcnt lgkmcnt(0)
	s_add_u32 s28, s28, s6
	v_lshlrev_b64 v[68:69], 12, v[68:69]
	s_addc_u32 s29, s29, s34
	s_lshl_b64 s[6:7], s[8:9], 2
	v_ashrrev_i32_e32 v67, 31, v66
	v_cndmask_b32_e64 v67, 0, v67, s[40:41]
	v_and_b32_e32 v120, 63, v116
	v_or_b32_e32 v117, 64, v120
	v_mov_b32_e32 v73, v193
	v_or_b32_e32 v118, 0x80, v120
	v_mov_b32_e32 v77, v193
	v_or_b32_e32 v119, 0xc0, v120
	v_or_b32_e32 v124, 0x100, v120
	v_or_b32_e32 v125, 0x140, v120
	v_lshlrev_b32_e32 v122, 7, v116
	v_and_b32_e32 v123, 0xffffe000, v122
	v_or_b32_e32 v153, 0x180, v120
	v_or_b32_e32 v160, 0x1c0, v120
	v_bfe_u32 v121, v116, 5, 1
	v_lshrrev_b32_e32 v104, 3, v160
	v_add_u32_e32 v161, 32, v123
	v_and_b32_e32 v122, 0xf80, v122
	v_xor_b32_e32 v110, v104, v116
	v_add_u32_e32 v122, v161, v122
	v_and_b32_e32 v123, 7, v116
	s_add_u32 s8, s28, s6
	v_mov_b32_e32 v87, v193
	v_mov_b32_e32 v89, v193
	s_addc_u32 s9, s29, s7
	v_mov_b32_e32 v91, v193
	v_mov_b32_e32 v93, v193
	v_mov_b32_e32 v97, v193
	v_mov_b32_e32 v99, v193
	v_lshlrev_b32_e32 v104, 12, v104
	v_mov_b32_e32 v105, v193
	v_lshlrev_b32_e32 v110, 4, v110
	v_mov_b32_e32 v103, v193
	v_and_b32_e32 v110, 0x70, v110
	v_mov_b32_e32 v111, v193
	v_lshl_add_u32 v156, v124, 4, v161
	v_lshl_add_u32 v155, v125, 4, v161
	v_lshl_add_u32 v152, v120, 4, v161
	v_lshl_add_u32 v159, v117, 4, v161
	v_lshl_add_u32 v158, v118, 4, v161
	v_lshl_add_u32 v157, v119, 4, v161
	v_lshl_add_u32 v154, v153, 4, v161
	s_waitcnt vmcnt(0)
	v_lshl_add_u64 v[70:71], v[70:71], 0, v[64:65]
	v_and_b32_e32 v64, 64, v116
	v_lshl_add_u64 v[68:69], v[70:71], 0, v[68:69]
	v_lshlrev_b32_e32 v192, 2, v64
	v_lshl_add_u64 v[68:69], v[68:69], 0, s[6:7]
	v_lshl_add_u64 v[106:107], v[68:69], 0, v[192:193]
	v_add_u32_e32 v70, 0xfffff800, v66
	v_mov_b32_e32 v68, s59
	v_mov_b32_e32 v69, s57
	v_cndmask_b32_e64 v69, v68, v69, s[40:41]
	v_mov_b32_e32 v68, s58
	v_mov_b32_e32 v71, s56
	v_cndmask_b32_e64 v66, v70, v66, s[40:41]
	v_cndmask_b32_e64 v70, 20, 23, s[40:41]
	v_cndmask_b32_e64 v68, v68, v71, s[40:41]
	v_lshlrev_b64 v[70:71], v70, s[4:5]
	v_lshl_add_u64 v[68:69], v[68:69], 0, v[70:71]
	v_lshlrev_b64 v[66:67], 12, v[66:67]
	v_lshl_add_u64 v[66:67], v[68:69], 0, v[66:67]
	v_lshl_add_u64 v[114:115], v[66:67], 0, s[6:7]
	v_bfe_u32 v66, v116, 3, 3
	v_xor_b32_e32 v68, v66, v116
	v_lshlrev_b32_e32 v66, 12, v66
	v_mov_b32_e32 v67, v193
	v_lshlrev_b32_e32 v68, 4, v68
	v_lshl_add_u64 v[70:71], v[106:107], 0, v[66:67]
	v_and_b32_e32 v68, 0x70, v68
	v_mov_b32_e32 v69, v193
	v_lshl_add_u64 v[112:113], v[70:71], 0, v[68:69]
	v_lshrrev_b32_e32 v70, 3, v117
	v_xor_b32_e32 v72, v70, v116
	v_lshlrev_b32_e32 v70, 12, v70
	v_mov_b32_e32 v71, v193
	v_lshlrev_b32_e32 v72, 4, v72
	v_lshl_add_u64 v[74:75], v[106:107], 0, v[70:71]
	v_and_b32_e32 v72, 0x70, v72
	v_lshl_add_u64 v[108:109], v[74:75], 0, v[72:73]
	v_lshrrev_b32_e32 v74, 3, v118
	v_xor_b32_e32 v76, v74, v116
	v_lshlrev_b32_e32 v74, 12, v74
	v_mov_b32_e32 v75, v193
	v_lshlrev_b32_e32 v76, 4, v76
	v_lshl_add_u64 v[78:79], v[106:107], 0, v[74:75]
	v_and_b32_e32 v76, 0x70, v76
	v_lshl_add_u64 v[100:101], v[78:79], 0, v[76:77]
	v_lshrrev_b32_e32 v78, 3, v119
	v_xor_b32_e32 v82, v78, v116
	v_lshlrev_b32_e32 v82, 4, v82
	v_and_b32_e32 v86, 0x70, v82
	v_lshrrev_b32_e32 v82, 3, v124
	v_xor_b32_e32 v84, v82, v116
	v_lshlrev_b32_e32 v84, 4, v84
	v_and_b32_e32 v90, 0x70, v84
	v_lshrrev_b32_e32 v84, 3, v125
	v_xor_b32_e32 v94, v84, v116
	v_lshlrev_b32_e32 v94, 4, v94
	v_and_b32_e32 v96, 0x70, v94
	v_lshrrev_b32_e32 v94, 3, v153
	v_xor_b32_e32 v102, v94, v116
	v_bitop3_b32 v116, v121, v116, 7 bitop3:0x78
	v_lshl_add_u32 v148, v116, 4, v122
	ds_write_b128 v148, v[48:51]
	v_bitop3_b32 v48, v121, v123, 2 bitop3:0x36
	v_lshl_add_u32 v149, v48, 4, v122
	v_bitop3_b32 v48, v121, v123, 4 bitop3:0x36
	v_lshl_add_u32 v150, v48, 4, v122
	v_bitop3_b32 v48, v121, v123, 6 bitop3:0x36
	v_lshl_add_u64 v[114:115], v[114:115], 0, v[192:193]
	v_lshl_add_u32 v151, v48, 4, v122
	ds_write_b128 v149, v[52:55]
	ds_write_b128 v150, v[56:59]
	ds_write_b128 v151, v[60:63]
	ds_write_b128 v148, v[32:35] offset:4096
	ds_write_b128 v149, v[36:39] offset:4096
	ds_write_b128 v150, v[40:43] offset:4096
	ds_write_b128 v151, v[44:47] offset:4096
	v_lshl_add_u64 v[32:33], v[114:115], 0, v[66:67]
	v_lshl_add_u64 v[144:145], v[32:33], 0, v[68:69]
	v_lshl_add_u64 v[32:33], v[114:115], 0, v[70:71]
	v_lshlrev_b32_e32 v78, 12, v78
	v_mov_b32_e32 v79, v193
	v_lshl_add_u64 v[140:141], v[32:33], 0, v[72:73]
	v_lshl_add_u64 v[32:33], v[114:115], 0, v[74:75]
	v_lshlrev_b32_e32 v88, 12, v82
	v_lshl_add_u64 v[136:137], v[32:33], 0, v[76:77]
	v_lshl_add_u64 v[32:33], v[114:115], 0, v[78:79]
	v_lshlrev_b32_e32 v92, 12, v84
	v_lshl_add_u64 v[132:133], v[32:33], 0, v[86:87]
	v_lshl_add_u64 v[32:33], v[114:115], 0, v[88:89]
	v_lshl_add_u64 v[64:65], s[8:9], 0, v[192:193]
	v_lshlrev_b32_e32 v98, 12, v94
	v_lshlrev_b32_e32 v102, 4, v102
	v_lshl_add_u64 v[128:129], v[32:33], 0, v[90:91]
	v_lshl_add_u64 v[32:33], v[114:115], 0, v[92:93]
	v_lshl_add_u64 v[64:65], v[64:65], 0, s[16:17]
	v_lshl_add_u64 v[80:81], v[106:107], 0, v[78:79]
	v_lshl_add_u64 v[82:83], v[106:107], 0, v[88:89]
	v_lshl_add_u64 v[84:85], v[106:107], 0, v[92:93]
	v_lshl_add_u64 v[94:95], v[106:107], 0, v[98:99]
	v_and_b32_e32 v102, 0x70, v102
; template <int TJ>
; DI void outproj_tile(const Params& p, int l, char* smem, int b, int trow0, int n0) {
;     ...
; #pragma unroll
;     for (int i = 0; i < 2; ++i)
; #pragma unroll
;         for (int it = 0; it < 4 * TJ; ++it) {
;             const int c = lane + 64 * it, row = c >> 3, f = 32 * i + 4 * ((c & 7) ^ (row & 7));
;             xo[i][it] = *(const float4*)(xs + (size_t)row * D + f);
;         }
; #pragma unroll
;     for (int i = 0; i < 2; ++i) {
; #pragma unroll
;         for (int j = 0; j < TJ; ++j)
; #pragma unroll
;             for (int q = 0; q < 4; ++q) {
;                 const int row = 32 * j + r, c16 = 2 * q + h;
;                 float4 y; y.x = acc[i][j][4 * q]; y.y = acc[i][j][4 * q + 1]; y.z = acc[i][j][4 * q + 2]; y.w = acc[i][j][4 * q + 3];
;                 *(float4*)(sb + row * 128 + ((c16 ^ (row & 7)) << 4)) = y;
;             }
; #pragma unroll
;         for (int it = 0; it < 4 * TJ; ++it) {
;             const int c = lane + 64 * it, row = c >> 3, f = 32 * i + 4 * ((c & 7) ^ (row & 7));
;             const float4 y = *(const float4*)(sb + c * 16);
;             const float4 g4 = *(const float4*)(gt + f);
;             float4 o;
;             o.x = xo[i][it].x + g4.x * y.x; o.y = xo[i][it].y + g4.y * y.y; o.z = xo[i][it].z + g4.z * y.z; o.w = xo[i][it].w + g4.w * y.w;
;             *(float4*)(xd + (size_t)row * D + f) = o;
;         }
;     }
	v_lshl_add_u64 v[106:107], v[106:107], 0, v[104:105]
	v_lshl_add_u64 v[124:125], v[32:33], 0, v[96:97]
	v_lshl_add_u64 v[32:33], v[114:115], 0, v[98:99]
	v_lshl_add_u64 v[80:81], v[80:81], 0, v[86:87]
	v_lshl_add_u64 v[82:83], v[82:83], 0, v[90:91]
	v_lshl_add_u64 v[84:85], v[84:85], 0, v[96:97]
	v_lshl_add_u64 v[94:95], v[94:95], 0, v[102:103]
	v_lshl_add_u64 v[106:107], v[106:107], 0, v[110:111]
	v_lshl_add_u64 v[146:147], v[64:65], 0, v[68:69]
	v_lshl_add_u64 v[120:121], v[32:33], 0, v[102:103]
	v_lshl_add_u64 v[32:33], v[114:115], 0, v[104:105]
	v_lshl_add_u64 v[142:143], v[64:65], 0, v[72:73]
	v_lshl_add_u64 v[138:139], v[64:65], 0, v[76:77]
	v_lshl_add_u64 v[134:135], v[64:65], 0, v[86:87]
	v_lshl_add_u64 v[130:131], v[64:65], 0, v[90:91]
	v_lshl_add_u64 v[126:127], v[64:65], 0, v[96:97]
	v_lshl_add_u64 v[122:123], v[64:65], 0, v[102:103]
	v_lshl_add_u64 v[118:119], v[64:65], 0, v[110:111]
	v_lshl_add_u64 v[116:117], v[32:33], 0, v[110:111]
	global_load_dwordx4 v[60:63], v[106:107], off nt
	global_load_dwordx4 v[32:35], v[106:107], off offset:128 nt
	global_load_dwordx4 v[64:67], v[94:95], off nt
	global_load_dwordx4 v[36:39], v[94:95], off offset:128 nt
	global_load_dwordx4 v[68:71], v[84:85], off nt
	global_load_dwordx4 v[40:43], v[84:85], off offset:128 nt
	global_load_dwordx4 v[76:79], v[82:83], off nt
	global_load_dwordx4 v[44:47], v[82:83], off offset:128 nt
	s_nop 0
	global_load_dwordx4 v[84:87], v[80:81], off nt
	ds_read_b128 v[88:91], v157
	global_load_dwordx4 v[48:51], v[80:81], off offset:128 nt
	global_load_dwordx4 v[92:95], v[100:101], off nt
	ds_read_b128 v[96:99], v158
	ds_read_b128 v[80:83], v156
	global_load_dwordx4 v[52:55], v[100:101], off offset:128 nt
	s_nop 0
	global_load_dwordx4 v[100:103], v[108:109], off nt
	ds_read_b128 v[104:107], v159
	ds_read_b128 v[72:75], v155
	global_load_dwordx4 v[56:59], v[108:109], off offset:128 nt
	s_nop 0
	global_load_dwordx4 v[108:111], v[112:113], off nt
	global_load_dwordx4 v[164:167], v[146:147], off
	v_lshl_add_u32 v153, v160, 4, v161
	ds_read_b128 v[160:163], v152
	global_load_dwordx4 v[112:115], v[112:113], off offset:128 nt
	s_waitcnt vmcnt(1) lgkmcnt(0)
	v_pk_fma_f32 v[108:109], v[160:161], v[164:165], v[108:109]
	v_pk_fma_f32 v[110:111], v[162:163], v[166:167], v[110:111]
	global_store_dwordx4 v[144:145], v[108:111], off nt
	global_load_dwordx4 v[108:111], v[142:143], off
	s_waitcnt vmcnt(0)
	v_pk_fma_f32 v[100:101], v[104:105], v[108:109], v[100:101]
	v_pk_fma_f32 v[102:103], v[106:107], v[110:111], v[102:103]
	global_store_dwordx4 v[140:141], v[100:103], off nt
	global_load_dwordx4 v[100:103], v[138:139], off
	s_waitcnt vmcnt(0)
	v_pk_fma_f32 v[92:93], v[96:97], v[100:101], v[92:93]
	v_pk_fma_f32 v[94:95], v[98:99], v[102:103], v[94:95]
	global_store_dwordx4 v[136:137], v[92:95], off nt
	global_load_dwordx4 v[92:95], v[134:135], off
	s_waitcnt vmcnt(0)
	v_pk_fma_f32 v[84:85], v[88:89], v[92:93], v[84:85]
	v_pk_fma_f32 v[86:87], v[90:91], v[94:95], v[86:87]
	global_store_dwordx4 v[132:133], v[84:87], off nt
	global_load_dwordx4 v[84:87], v[130:131], off
	s_waitcnt vmcnt(0)
	v_pk_fma_f32 v[76:77], v[80:81], v[84:85], v[76:77]
	v_pk_fma_f32 v[78:79], v[82:83], v[86:87], v[78:79]
	global_store_dwordx4 v[128:129], v[76:79], off nt
	global_load_dwordx4 v[76:79], v[126:127], off
	s_waitcnt vmcnt(0)
	v_pk_fma_f32 v[68:69], v[72:73], v[76:77], v[68:69]
	v_pk_fma_f32 v[70:71], v[74:75], v[78:79], v[70:71]
	global_store_dwordx4 v[124:125], v[68:71], off nt
	global_load_dwordx4 v[72:75], v[122:123], off
	ds_read_b128 v[68:71], v154
	s_waitcnt vmcnt(0) lgkmcnt(0)
	v_pk_fma_f32 v[64:65], v[68:69], v[72:73], v[64:65]
	v_pk_fma_f32 v[66:67], v[70:71], v[74:75], v[66:67]
	global_store_dwordx4 v[120:121], v[64:67], off nt
	global_load_dwordx4 v[68:71], v[118:119], off
	ds_read_b128 v[64:67], v153
	s_waitcnt vmcnt(0) lgkmcnt(0)
	v_pk_fma_f32 v[60:61], v[64:65], v[68:69], v[60:61]
	v_pk_fma_f32 v[62:63], v[66:67], v[70:71], v[62:63]
	global_store_dwordx4 v[116:117], v[60:63], off nt
	ds_write_b128 v148, v[16:19]
	ds_write_b128 v149, v[20:23]
	ds_write_b128 v150, v[24:27]
	ds_write_b128 v151, v[28:31]
	ds_write_b128 v148, v[0:3] offset:4096
	ds_write_b128 v149, v[4:7] offset:4096
	ds_write_b128 v150, v[8:11] offset:4096
	ds_write_b128 v151, v[12:15] offset:4096
	global_load_dwordx4 v[4:7], v[146:147], off offset:128
	ds_read_b128 v[0:3], v152
	s_waitcnt vmcnt(0) lgkmcnt(0)
	v_pk_fma_f32 v[0:1], v[0:1], v[4:5], v[112:113]
	v_pk_fma_f32 v[2:3], v[2:3], v[6:7], v[114:115]
	global_store_dwordx4 v[144:145], v[0:3], off offset:128 nt
	global_load_dwordx4 v[4:7], v[142:143], off offset:128
	ds_read_b128 v[0:3], v159
	s_waitcnt vmcnt(0) lgkmcnt(0)
	v_pk_fma_f32 v[0:1], v[0:1], v[4:5], v[56:57]
	v_pk_fma_f32 v[2:3], v[2:3], v[6:7], v[58:59]
	global_store_dwordx4 v[140:141], v[0:3], off offset:128 nt
	global_load_dwordx4 v[4:7], v[138:139], off offset:128
	ds_read_b128 v[0:3], v158
	s_waitcnt vmcnt(0) lgkmcnt(0)
	v_pk_fma_f32 v[0:1], v[0:1], v[4:5], v[52:53]
	v_pk_fma_f32 v[2:3], v[2:3], v[6:7], v[54:55]
	global_store_dwordx4 v[136:137], v[0:3], off offset:128 nt
	global_load_dwordx4 v[4:7], v[134:135], off offset:128
	ds_read_b128 v[0:3], v157
	s_waitcnt vmcnt(0) lgkmcnt(0)
	v_pk_fma_f32 v[0:1], v[0:1], v[4:5], v[48:49]
	v_pk_fma_f32 v[2:3], v[2:3], v[6:7], v[50:51]
	global_store_dwordx4 v[132:133], v[0:3], off offset:128 nt
	global_load_dwordx4 v[4:7], v[130:131], off offset:128
	ds_read_b128 v[0:3], v156
	s_waitcnt vmcnt(0) lgkmcnt(0)
	v_pk_fma_f32 v[0:1], v[0:1], v[4:5], v[44:45]
	v_pk_fma_f32 v[2:3], v[2:3], v[6:7], v[46:47]
	global_store_dwordx4 v[128:129], v[0:3], off offset:128 nt
	global_load_dwordx4 v[4:7], v[126:127], off offset:128
	ds_read_b128 v[0:3], v155
	s_waitcnt vmcnt(0) lgkmcnt(0)
	v_pk_fma_f32 v[0:1], v[0:1], v[4:5], v[40:41]
	v_pk_fma_f32 v[2:3], v[2:3], v[6:7], v[42:43]
	global_store_dwordx4 v[124:125], v[0:3], off offset:128 nt
	global_load_dwordx4 v[4:7], v[122:123], off offset:128
	ds_read_b128 v[0:3], v154
	s_waitcnt vmcnt(0) lgkmcnt(0)
	v_pk_fma_f32 v[0:1], v[0:1], v[4:5], v[36:37]
	v_pk_fma_f32 v[2:3], v[2:3], v[6:7], v[38:39]
	global_store_dwordx4 v[120:121], v[0:3], off offset:128 nt
	global_load_dwordx4 v[4:7], v[118:119], off offset:128
	ds_read_b128 v[0:3], v153
	s_waitcnt vmcnt(0) lgkmcnt(0)
	v_pk_fma_f32 v[0:1], v[0:1], v[4:5], v[32:33]
	v_pk_fma_f32 v[2:3], v[2:3], v[6:7], v[34:35]
	global_store_dwordx4 v[116:117], v[0:3], off offset:128 nt
